# v25: gate-tile ratio sigmoid(g_a)/sigmoid(g_b) formed as sigmoid(g_a)*min(1+exp(-g_b),1e20) instead of rcp(max(rcp(1+exp(-g_b)),1e-20)): one reciprocal and one max fewer per value, same function, f32
# speedup vs baseline: 1.0020x; 1.0020x over previous
; __device__ __forceinline__ f32x4 sigm4(f32x4 v) { return (f32x4){sigmoid_f(v[0]), sigmoid_f(v[1]), sigmoid_f(v[2]), sigmoid_f(v[3])}; }
;     __device__ __forceinline__ void operator()(const f32x4 (&acc)[2][2][4][2], const pg8::Unit& u, int wr, int wc, int fr, int fq) const {
;     ...
;                         if (act == 5) { v0 = sigm4(v0); v1 = sigm4(v1);
;                             if (bj == 0) { const f32x4 b0 = sigm4(acc[ai][1][m][0]), b1 = sigm4(acc[ai][1][m][1]);
; #pragma unroll
;                                 for (int e = 0; e < 4; ++e) { v0[e] *= __builtin_amdgcn_rcpf(fmaxf(b0[e], 1e-20f)); v1[e] *= __builtin_amdgcn_rcpf(fmaxf(b1[e], 1e-20f)); } } }
.LBB0_198:
	s_andn2_b64 vcc, exec, s[16:17]
	s_cbranch_vccnz .LBB0_200
	v_mul_f32_e32 v147, 0xbfb8aa3b, v116
	v_exp_f32_e32 v147, v147
	v_mul_f32_e32 v148, 0xbfb8aa3b, v117
	v_exp_f32_e32 v148, v148
	v_mul_f32_e32 v152, 0xbfb8aa3b, v119
	v_add_f32_e32 v147, 1.0, v147
	v_exp_f32_e32 v153, v152
	v_add_f32_e32 v149, 1.0, v148
	v_rcp_f32_e32 v148, v147
	v_mul_f32_e32 v147, 0xbfb8aa3b, v118
	v_exp_f32_e32 v147, v147
	v_mul_f32_e32 v160, 0xbfb8aa3b, v123
	v_exp_f32_e32 v160, v160
	v_mul_f32_e32 v168, 0xbfb8aa3b, v115
	v_add_f32_e32 v147, 1.0, v147
	v_rcp_f32_e32 v152, v147
	v_add_f32_e32 v147, 1.0, v153
	v_mul_f32_e32 v153, 0xbfb8aa3b, v124
	v_exp_f32_e32 v154, v153
	v_mul_f32_e32 v153, 0xbfb8aa3b, v125
	v_exp_f32_e32 v155, v153
	v_rcp_f32_e32 v153, v147
	v_add_f32_e32 v147, 1.0, v154
	v_rcp_f32_e32 v154, v147
	v_add_f32_e32 v147, 1.0, v155
	v_mul_f32_e32 v155, 0xbfb8aa3b, v126
	v_exp_f32_e32 v156, v155
	v_mul_f32_e32 v155, 0xbfb8aa3b, v127
	v_exp_f32_e32 v157, v155
	v_rcp_f32_e32 v155, v147
	v_add_f32_e32 v147, 1.0, v156
	v_rcp_f32_e32 v156, v147
	v_add_f32_e32 v147, 1.0, v157
	v_mul_f32_e32 v157, 0xbfb8aa3b, v120
	v_exp_f32_e32 v158, v157
	v_mul_f32_e32 v157, 0xbfb8aa3b, v121
	v_exp_f32_e32 v159, v157
	v_rcp_f32_e32 v157, v147
	v_add_f32_e32 v147, 1.0, v158
	v_rcp_f32_e32 v240, v147
	v_min_f32_e32 v248, 0x60ad78ec, v147
	v_add_f32_e32 v158, 1.0, v159
	v_mul_f32_e32 v159, 0xbfb8aa3b, v122
	v_exp_f32_e32 v159, v159
	v_rcp_f32_e32 v241, v158
	v_min_f32_e32 v249, 0x60ad78ec, v158
	v_exp_f32_e32 v168, v168
	v_add_f32_e32 v158, 1.0, v159
	v_mul_f32_e32 v159, 0xbfb8aa3b, v112
	v_rcp_f32_e32 v242, v158
	v_min_f32_e32 v250, 0x60ad78ec, v158
	v_add_f32_e32 v158, 1.0, v160
	v_exp_f32_e32 v159, v159
	v_mul_f32_e32 v160, 0xbfb8aa3b, v113
	v_exp_f32_e32 v160, v160
	v_rcp_f32_e32 v243, v158
	v_min_f32_e32 v251, 0x60ad78ec, v158
	v_add_f32_e32 v158, 1.0, v159
	v_rcp_f32_e32 v244, v158
	v_min_f32_e32 v252, 0x60ad78ec, v158
	v_add_f32_e32 v158, 1.0, v160
	v_mul_f32_e32 v160, 0xbfb8aa3b, v114
	v_exp_f32_e32 v160, v160
	v_rcp_f32_e32 v245, v158
	v_min_f32_e32 v253, 0x60ad78ec, v158
	v_rcp_f32_e32 v149, v149
	v_add_f32_e32 v158, 1.0, v160
	v_rcp_f32_e32 v246, v158
	v_min_f32_e32 v254, 0x60ad78ec, v158
	v_add_f32_e32 v158, 1.0, v168
	v_rcp_f32_e32 v247, v158
	v_min_f32_e32 v255, 0x60ad78ec, v158
	v_pk_mul_f32 v[154:155], v[154:155], v[248:249]
	v_pk_mul_f32 v[156:157], v[156:157], v[250:251]
	v_pk_mul_f32 v[158:159], v[148:149], v[252:253]
	v_pk_mul_f32 v[160:161], v[152:153], v[254:255]

; __device__ __forceinline__ f32x4 sigm4(f32x4 v) { return (f32x4){sigmoid_f(v[0]), sigmoid_f(v[1]), sigmoid_f(v[2]), sigmoid_f(v[3])}; }
;     __device__ __forceinline__ void operator()(const f32x4 (&acc)[2][2][4][2], const pg8::Unit& u, int wr, int wc, int fr, int fq) const {
;     ...
;                         if (act == 5) { v0 = sigm4(v0); v1 = sigm4(v1);
;                             if (bj == 0) { const f32x4 b0 = sigm4(acc[ai][1][m][0]), b1 = sigm4(acc[ai][1][m][1]);
; #pragma unroll
;                                 for (int e = 0; e < 4; ++e) { v0[e] *= __builtin_amdgcn_rcpf(fmaxf(b0[e], 1e-20f)); v1[e] *= __builtin_amdgcn_rcpf(fmaxf(b1[e], 1e-20f)); } } }
.LBB0_226:
	s_andn2_b64 vcc, exec, s[16:17]
	s_cbranch_vccnz .LBB0_228
	v_mul_f32_e32 v147, 0xbfb8aa3b, v100
	v_exp_f32_e32 v147, v147
	v_mul_f32_e32 v152, 0xbfb8aa3b, v101
	v_exp_f32_e32 v152, v152
	v_mul_f32_e32 v154, 0xbfb8aa3b, v103
	v_add_f32_e32 v147, 1.0, v147
	v_exp_f32_e32 v154, v154
	v_add_f32_e32 v153, 1.0, v152
	v_rcp_f32_e32 v152, v147
	v_mul_f32_e32 v147, 0xbfb8aa3b, v102
	v_exp_f32_e32 v147, v147
	v_mul_f32_e32 v155, 0xbfb8aa3b, v109
	v_exp_f32_e32 v155, v155
	v_mul_f32_e32 v167, 0xbfb8aa3b, v107
	v_add_f32_e32 v147, 1.0, v147
	v_rcp_f32_e32 v160, v147
	v_add_f32_e32 v147, 1.0, v154
	v_mul_f32_e32 v154, 0xbfb8aa3b, v108
	v_exp_f32_e32 v154, v154
	v_rcp_f32_e32 v161, v147
	v_exp_f32_e32 v167, v167
	v_mul_f32_e32 v168, 0xbfb8aa3b, v99
	v_add_f32_e32 v147, 1.0, v154
	v_rcp_f32_e32 v154, v147
	v_add_f32_e32 v147, 1.0, v155
	v_mul_f32_e32 v155, 0xbfb8aa3b, v110
	v_exp_f32_e32 v156, v155
	v_mul_f32_e32 v155, 0xbfb8aa3b, v111
	v_exp_f32_e32 v157, v155
	v_rcp_f32_e32 v155, v147
	v_add_f32_e32 v147, 1.0, v156
	v_rcp_f32_e32 v156, v147
	v_add_f32_e32 v147, 1.0, v157
	v_mul_f32_e32 v157, 0xbfb8aa3b, v104
	v_exp_f32_e32 v158, v157
	v_mul_f32_e32 v157, 0xbfb8aa3b, v105
	v_exp_f32_e32 v159, v157
	v_rcp_f32_e32 v157, v147
	v_add_f32_e32 v147, 1.0, v158
	v_rcp_f32_e32 v240, v147
	v_min_f32_e32 v248, 0x60ad78ec, v147
	v_add_f32_e32 v158, 1.0, v159
	v_mul_f32_e32 v159, 0xbfb8aa3b, v106
	v_exp_f32_e32 v159, v159
	v_rcp_f32_e32 v241, v158
	v_min_f32_e32 v249, 0x60ad78ec, v158
	v_exp_f32_e32 v168, v168
	v_add_f32_e32 v158, 1.0, v159
	v_mul_f32_e32 v159, 0xbfb8aa3b, v96
	v_rcp_f32_e32 v242, v158
	v_min_f32_e32 v250, 0x60ad78ec, v158
	v_add_f32_e32 v158, 1.0, v167
	v_exp_f32_e32 v159, v159
	v_mul_f32_e32 v167, 0xbfb8aa3b, v97
	v_exp_f32_e32 v167, v167
	v_rcp_f32_e32 v243, v158
	v_min_f32_e32 v251, 0x60ad78ec, v158
	v_add_f32_e32 v158, 1.0, v159
	v_rcp_f32_e32 v244, v158
	v_min_f32_e32 v252, 0x60ad78ec, v158
	v_add_f32_e32 v158, 1.0, v167
	v_mul_f32_e32 v167, 0xbfb8aa3b, v98
	v_exp_f32_e32 v167, v167
	v_rcp_f32_e32 v245, v158
	v_min_f32_e32 v253, 0x60ad78ec, v158
	v_rcp_f32_e32 v153, v153
	v_add_f32_e32 v158, 1.0, v167
	v_rcp_f32_e32 v246, v158
	v_min_f32_e32 v254, 0x60ad78ec, v158
	v_add_f32_e32 v158, 1.0, v168
	v_rcp_f32_e32 v247, v158
	v_min_f32_e32 v255, 0x60ad78ec, v158
	v_pk_mul_f32 v[154:155], v[154:155], v[248:249]
	v_pk_mul_f32 v[156:157], v[156:157], v[250:251]
	v_pk_mul_f32 v[158:159], v[152:153], v[252:253]
	v_pk_mul_f32 v[160:161], v[160:161], v[254:255]

; __device__ __forceinline__ f32x4 sigm4(f32x4 v) { return (f32x4){sigmoid_f(v[0]), sigmoid_f(v[1]), sigmoid_f(v[2]), sigmoid_f(v[3])}; }
;     __device__ __forceinline__ void operator()(const f32x4 (&acc)[2][2][4][2], const pg8::Unit& u, int wr, int wc, int fr, int fq) const {
;     ...
;                         if (act == 5) { v0 = sigm4(v0); v1 = sigm4(v1);
;                             if (bj == 0) { const f32x4 b0 = sigm4(acc[ai][1][m][0]), b1 = sigm4(acc[ai][1][m][1]);
; #pragma unroll
;                                 for (int e = 0; e < 4; ++e) { v0[e] *= __builtin_amdgcn_rcpf(fmaxf(b0[e], 1e-20f)); v1[e] *= __builtin_amdgcn_rcpf(fmaxf(b1[e], 1e-20f)); } } }
.LBB0_254:
	s_andn2_b64 vcc, exec, s[16:17]
	s_cbranch_vccnz .LBB0_256
	v_mul_f32_e32 v147, 0xbfb8aa3b, v84
	v_exp_f32_e32 v147, v147
	v_mul_f32_e32 v152, 0xbfb8aa3b, v85
	v_exp_f32_e32 v152, v152
	v_mul_f32_e32 v154, 0xbfb8aa3b, v87
	v_add_f32_e32 v147, 1.0, v147
	v_exp_f32_e32 v154, v154
	v_add_f32_e32 v153, 1.0, v152
	v_rcp_f32_e32 v152, v147
	v_mul_f32_e32 v147, 0xbfb8aa3b, v86
	v_exp_f32_e32 v147, v147
	v_mul_f32_e32 v155, 0xbfb8aa3b, v93
	v_exp_f32_e32 v155, v155
	v_mul_f32_e32 v167, 0xbfb8aa3b, v91
	v_add_f32_e32 v147, 1.0, v147
	v_rcp_f32_e32 v160, v147
	v_add_f32_e32 v147, 1.0, v154
	v_mul_f32_e32 v154, 0xbfb8aa3b, v92
	v_exp_f32_e32 v154, v154
	v_rcp_f32_e32 v161, v147
	v_exp_f32_e32 v167, v167
	v_mul_f32_e32 v168, 0xbfb8aa3b, v83
	v_add_f32_e32 v147, 1.0, v154
	v_rcp_f32_e32 v154, v147
	v_add_f32_e32 v147, 1.0, v155
	v_mul_f32_e32 v155, 0xbfb8aa3b, v94
	v_exp_f32_e32 v156, v155
	v_mul_f32_e32 v155, 0xbfb8aa3b, v95
	v_exp_f32_e32 v157, v155
	v_rcp_f32_e32 v155, v147
	v_add_f32_e32 v147, 1.0, v156
	v_rcp_f32_e32 v156, v147
	v_add_f32_e32 v147, 1.0, v157
	v_mul_f32_e32 v157, 0xbfb8aa3b, v88
	v_exp_f32_e32 v158, v157
	v_mul_f32_e32 v157, 0xbfb8aa3b, v89
	v_exp_f32_e32 v159, v157
	v_rcp_f32_e32 v157, v147
	v_add_f32_e32 v147, 1.0, v158
	v_rcp_f32_e32 v240, v147
	v_min_f32_e32 v248, 0x60ad78ec, v147
	v_add_f32_e32 v158, 1.0, v159
	v_mul_f32_e32 v159, 0xbfb8aa3b, v90
	v_exp_f32_e32 v159, v159
	v_rcp_f32_e32 v241, v158
	v_min_f32_e32 v249, 0x60ad78ec, v158
	v_exp_f32_e32 v168, v168
	v_add_f32_e32 v158, 1.0, v159
	v_mul_f32_e32 v159, 0xbfb8aa3b, v80
	v_rcp_f32_e32 v242, v158
	v_min_f32_e32 v250, 0x60ad78ec, v158
	v_add_f32_e32 v158, 1.0, v167
	v_exp_f32_e32 v159, v159
	v_mul_f32_e32 v167, 0xbfb8aa3b, v81
	v_exp_f32_e32 v167, v167
	v_rcp_f32_e32 v243, v158
	v_min_f32_e32 v251, 0x60ad78ec, v158
	v_add_f32_e32 v158, 1.0, v159
	v_rcp_f32_e32 v244, v158
	v_min_f32_e32 v252, 0x60ad78ec, v158
	v_add_f32_e32 v158, 1.0, v167
	v_mul_f32_e32 v167, 0xbfb8aa3b, v82
	v_exp_f32_e32 v167, v167
	v_rcp_f32_e32 v245, v158
	v_min_f32_e32 v253, 0x60ad78ec, v158
	v_rcp_f32_e32 v153, v153
	v_add_f32_e32 v158, 1.0, v167
	v_rcp_f32_e32 v246, v158
	v_min_f32_e32 v254, 0x60ad78ec, v158
	v_add_f32_e32 v158, 1.0, v168
	v_rcp_f32_e32 v247, v158
	v_min_f32_e32 v255, 0x60ad78ec, v158
	v_pk_mul_f32 v[154:155], v[154:155], v[248:249]
	v_pk_mul_f32 v[156:157], v[156:157], v[250:251]
	v_pk_mul_f32 v[158:159], v[152:153], v[252:253]
	v_pk_mul_f32 v[160:161], v[160:161], v[254:255]

; __device__ __forceinline__ f32x4 sigm4(f32x4 v) { return (f32x4){sigmoid_f(v[0]), sigmoid_f(v[1]), sigmoid_f(v[2]), sigmoid_f(v[3])}; }
;     __device__ __forceinline__ void operator()(const f32x4 (&acc)[2][2][4][2], const pg8::Unit& u, int wr, int wc, int fr, int fq) const {
;     ...
;                         if (act == 5) { v0 = sigm4(v0); v1 = sigm4(v1);
;                             if (bj == 0) { const f32x4 b0 = sigm4(acc[ai][1][m][0]), b1 = sigm4(acc[ai][1][m][1]);
; #pragma unroll
;                                 for (int e = 0; e < 4; ++e) { v0[e] *= __builtin_amdgcn_rcpf(fmaxf(b0[e], 1e-20f)); v1[e] *= __builtin_amdgcn_rcpf(fmaxf(b1[e], 1e-20f)); } } }
.LBB0_282:
	s_andn2_b64 vcc, exec, s[16:17]
	s_cbranch_vccnz .LBB0_284
	v_mul_f32_e32 v147, 0xbfb8aa3b, v68
	v_exp_f32_e32 v147, v147
	v_mul_f32_e32 v152, 0xbfb8aa3b, v69
	v_exp_f32_e32 v152, v152
	v_mul_f32_e32 v154, 0xbfb8aa3b, v71
	v_add_f32_e32 v147, 1.0, v147
	v_exp_f32_e32 v154, v154
	v_add_f32_e32 v153, 1.0, v152
	v_rcp_f32_e32 v152, v147
	v_mul_f32_e32 v147, 0xbfb8aa3b, v70
	v_exp_f32_e32 v147, v147
	v_mul_f32_e32 v155, 0xbfb8aa3b, v77
	v_exp_f32_e32 v155, v155
	v_mul_f32_e32 v167, 0xbfb8aa3b, v75
	v_add_f32_e32 v147, 1.0, v147
	v_rcp_f32_e32 v160, v147
	v_add_f32_e32 v147, 1.0, v154
	v_mul_f32_e32 v154, 0xbfb8aa3b, v76
	v_exp_f32_e32 v154, v154
	v_rcp_f32_e32 v161, v147
	v_exp_f32_e32 v167, v167
	v_mul_f32_e32 v168, 0xbfb8aa3b, v67
	v_add_f32_e32 v147, 1.0, v154
	v_rcp_f32_e32 v154, v147
	v_add_f32_e32 v147, 1.0, v155
	v_mul_f32_e32 v155, 0xbfb8aa3b, v78
	v_exp_f32_e32 v156, v155
	v_mul_f32_e32 v155, 0xbfb8aa3b, v79
	v_exp_f32_e32 v157, v155
	v_rcp_f32_e32 v155, v147
	v_add_f32_e32 v147, 1.0, v156
	v_rcp_f32_e32 v156, v147
	v_add_f32_e32 v147, 1.0, v157
	v_mul_f32_e32 v157, 0xbfb8aa3b, v72
	v_exp_f32_e32 v158, v157
	v_mul_f32_e32 v157, 0xbfb8aa3b, v73
	v_exp_f32_e32 v159, v157
	v_rcp_f32_e32 v157, v147
	v_add_f32_e32 v147, 1.0, v158
	v_rcp_f32_e32 v240, v147
	v_min_f32_e32 v248, 0x60ad78ec, v147
	v_add_f32_e32 v158, 1.0, v159
	v_mul_f32_e32 v159, 0xbfb8aa3b, v74
	v_exp_f32_e32 v159, v159
	v_rcp_f32_e32 v241, v158
	v_min_f32_e32 v249, 0x60ad78ec, v158
	v_exp_f32_e32 v168, v168
	v_add_f32_e32 v158, 1.0, v159
	v_mul_f32_e32 v159, 0xbfb8aa3b, v64
	v_rcp_f32_e32 v242, v158
	v_min_f32_e32 v250, 0x60ad78ec, v158
	v_add_f32_e32 v158, 1.0, v167
	v_exp_f32_e32 v159, v159
	v_mul_f32_e32 v167, 0xbfb8aa3b, v65
	v_exp_f32_e32 v167, v167
	v_rcp_f32_e32 v243, v158
	v_min_f32_e32 v251, 0x60ad78ec, v158
	v_add_f32_e32 v158, 1.0, v159
	v_rcp_f32_e32 v244, v158
	v_min_f32_e32 v252, 0x60ad78ec, v158
	v_add_f32_e32 v158, 1.0, v167
	v_mul_f32_e32 v167, 0xbfb8aa3b, v66
	v_exp_f32_e32 v167, v167
	v_rcp_f32_e32 v245, v158
	v_min_f32_e32 v253, 0x60ad78ec, v158
	v_rcp_f32_e32 v153, v153
	v_add_f32_e32 v158, 1.0, v167
	v_rcp_f32_e32 v246, v158
	v_min_f32_e32 v254, 0x60ad78ec, v158
	v_add_f32_e32 v158, 1.0, v168
	v_rcp_f32_e32 v247, v158
	v_min_f32_e32 v255, 0x60ad78ec, v158
	v_pk_mul_f32 v[154:155], v[154:155], v[248:249]
	v_pk_mul_f32 v[156:157], v[156:157], v[250:251]
	v_pk_mul_f32 v[158:159], v[152:153], v[252:253]
	v_pk_mul_f32 v[160:161], v[160:161], v[254:255]

; __device__ __forceinline__ f32x4 sigm4(f32x4 v) { return (f32x4){sigmoid_f(v[0]), sigmoid_f(v[1]), sigmoid_f(v[2]), sigmoid_f(v[3])}; }
;     __device__ __forceinline__ void operator()(const f32x4 (&acc)[2][2][4][2], const pg8::Unit& u, int wr, int wc, int fr, int fq) const {
;     ...
;                         if (act == 5) { v0 = sigm4(v0); v1 = sigm4(v1);
;                             if (bj == 0) { const f32x4 b0 = sigm4(acc[ai][1][m][0]), b1 = sigm4(acc[ai][1][m][1]);
; #pragma unroll
;                                 for (int e = 0; e < 4; ++e) { v0[e] *= __builtin_amdgcn_rcpf(fmaxf(b0[e], 1e-20f)); v1[e] *= __builtin_amdgcn_rcpf(fmaxf(b1[e], 1e-20f)); } } }
.LBB0_310:
	s_andn2_b64 vcc, exec, s[16:17]
	s_cbranch_vccnz .LBB0_312
	v_mul_f32_e32 v147, 0xbfb8aa3b, v52
	v_exp_f32_e32 v147, v147
	v_mul_f32_e32 v152, 0xbfb8aa3b, v53
	v_exp_f32_e32 v152, v152
	v_mul_f32_e32 v154, 0xbfb8aa3b, v55
	v_add_f32_e32 v147, 1.0, v147
	v_exp_f32_e32 v154, v154
	v_add_f32_e32 v153, 1.0, v152
	v_rcp_f32_e32 v152, v147
	v_mul_f32_e32 v147, 0xbfb8aa3b, v54
	v_exp_f32_e32 v147, v147
	v_mul_f32_e32 v155, 0xbfb8aa3b, v61
	v_exp_f32_e32 v155, v155
	v_mul_f32_e32 v167, 0xbfb8aa3b, v59
	v_add_f32_e32 v147, 1.0, v147
	v_rcp_f32_e32 v160, v147
	v_add_f32_e32 v147, 1.0, v154
	v_mul_f32_e32 v154, 0xbfb8aa3b, v60
	v_exp_f32_e32 v154, v154
	v_rcp_f32_e32 v161, v147
	v_exp_f32_e32 v167, v167
	v_mul_f32_e32 v168, 0xbfb8aa3b, v51
	v_add_f32_e32 v147, 1.0, v154
	v_rcp_f32_e32 v154, v147
	v_add_f32_e32 v147, 1.0, v155
	v_mul_f32_e32 v155, 0xbfb8aa3b, v62
	v_exp_f32_e32 v156, v155
	v_mul_f32_e32 v155, 0xbfb8aa3b, v63
	v_exp_f32_e32 v157, v155
	v_rcp_f32_e32 v155, v147
	v_add_f32_e32 v147, 1.0, v156
	v_rcp_f32_e32 v156, v147
	v_add_f32_e32 v147, 1.0, v157
	v_mul_f32_e32 v157, 0xbfb8aa3b, v56
	v_exp_f32_e32 v158, v157
	v_mul_f32_e32 v157, 0xbfb8aa3b, v57
	v_exp_f32_e32 v159, v157
	v_rcp_f32_e32 v157, v147
	v_add_f32_e32 v147, 1.0, v158
	v_rcp_f32_e32 v240, v147
	v_min_f32_e32 v248, 0x60ad78ec, v147
	v_add_f32_e32 v158, 1.0, v159
	v_mul_f32_e32 v159, 0xbfb8aa3b, v58
	v_exp_f32_e32 v159, v159
	v_rcp_f32_e32 v241, v158
	v_min_f32_e32 v249, 0x60ad78ec, v158
	v_exp_f32_e32 v168, v168
	v_add_f32_e32 v158, 1.0, v159
	v_mul_f32_e32 v159, 0xbfb8aa3b, v48
	v_rcp_f32_e32 v242, v158
	v_min_f32_e32 v250, 0x60ad78ec, v158
	v_add_f32_e32 v158, 1.0, v167
	v_exp_f32_e32 v159, v159
	v_mul_f32_e32 v167, 0xbfb8aa3b, v49
	v_exp_f32_e32 v167, v167
	v_rcp_f32_e32 v243, v158
	v_min_f32_e32 v251, 0x60ad78ec, v158
	v_add_f32_e32 v158, 1.0, v159
	v_rcp_f32_e32 v244, v158
	v_min_f32_e32 v252, 0x60ad78ec, v158
	v_add_f32_e32 v158, 1.0, v167
	v_mul_f32_e32 v167, 0xbfb8aa3b, v50
	v_exp_f32_e32 v167, v167
	v_rcp_f32_e32 v245, v158
	v_min_f32_e32 v253, 0x60ad78ec, v158
	v_rcp_f32_e32 v153, v153
	v_add_f32_e32 v158, 1.0, v167
	v_rcp_f32_e32 v246, v158
	v_min_f32_e32 v254, 0x60ad78ec, v158
	v_add_f32_e32 v158, 1.0, v168
	v_rcp_f32_e32 v247, v158
	v_min_f32_e32 v255, 0x60ad78ec, v158
	v_pk_mul_f32 v[154:155], v[154:155], v[248:249]
	v_pk_mul_f32 v[156:157], v[156:157], v[250:251]
	v_pk_mul_f32 v[158:159], v[152:153], v[252:253]
	v_pk_mul_f32 v[160:161], v[160:161], v[254:255]

; __device__ __forceinline__ f32x4 sigm4(f32x4 v) { return (f32x4){sigmoid_f(v[0]), sigmoid_f(v[1]), sigmoid_f(v[2]), sigmoid_f(v[3])}; }
;     __device__ __forceinline__ void operator()(const f32x4 (&acc)[2][2][4][2], const pg8::Unit& u, int wr, int wc, int fr, int fq) const {
;     ...
;                         if (act == 5) { v0 = sigm4(v0); v1 = sigm4(v1);
;                             if (bj == 0) { const f32x4 b0 = sigm4(acc[ai][1][m][0]), b1 = sigm4(acc[ai][1][m][1]);
; #pragma unroll
;                                 for (int e = 0; e < 4; ++e) { v0[e] *= __builtin_amdgcn_rcpf(fmaxf(b0[e], 1e-20f)); v1[e] *= __builtin_amdgcn_rcpf(fmaxf(b1[e], 1e-20f)); } } }
.LBB0_338:
	s_andn2_b64 vcc, exec, s[16:17]
	s_cbranch_vccnz .LBB0_340
	v_mul_f32_e32 v147, 0xbfb8aa3b, v36
	v_exp_f32_e32 v147, v147
	v_mul_f32_e32 v152, 0xbfb8aa3b, v37
	v_exp_f32_e32 v152, v152
	v_mul_f32_e32 v154, 0xbfb8aa3b, v39
	v_add_f32_e32 v147, 1.0, v147
	v_exp_f32_e32 v154, v154
	v_add_f32_e32 v153, 1.0, v152
	v_rcp_f32_e32 v152, v147
	v_mul_f32_e32 v147, 0xbfb8aa3b, v38
	v_exp_f32_e32 v147, v147
	v_mul_f32_e32 v155, 0xbfb8aa3b, v45
	v_exp_f32_e32 v155, v155
	v_mul_f32_e32 v167, 0xbfb8aa3b, v43
	v_add_f32_e32 v147, 1.0, v147
	v_rcp_f32_e32 v160, v147
	v_add_f32_e32 v147, 1.0, v154
	v_mul_f32_e32 v154, 0xbfb8aa3b, v44
	v_exp_f32_e32 v154, v154
	v_rcp_f32_e32 v161, v147
	v_exp_f32_e32 v167, v167
	v_mul_f32_e32 v168, 0xbfb8aa3b, v35
	v_add_f32_e32 v147, 1.0, v154
	v_rcp_f32_e32 v154, v147
	v_add_f32_e32 v147, 1.0, v155
	v_mul_f32_e32 v155, 0xbfb8aa3b, v46
	v_exp_f32_e32 v156, v155
	v_mul_f32_e32 v155, 0xbfb8aa3b, v47
	v_exp_f32_e32 v157, v155
	v_rcp_f32_e32 v155, v147
	v_add_f32_e32 v147, 1.0, v156
	v_rcp_f32_e32 v156, v147
	v_add_f32_e32 v147, 1.0, v157
	v_mul_f32_e32 v157, 0xbfb8aa3b, v40
	v_exp_f32_e32 v158, v157
	v_mul_f32_e32 v157, 0xbfb8aa3b, v41
	v_exp_f32_e32 v159, v157
	v_rcp_f32_e32 v157, v147
	v_add_f32_e32 v147, 1.0, v158
	v_rcp_f32_e32 v240, v147
	v_min_f32_e32 v248, 0x60ad78ec, v147
	v_add_f32_e32 v158, 1.0, v159
	v_mul_f32_e32 v159, 0xbfb8aa3b, v42
	v_exp_f32_e32 v159, v159
	v_rcp_f32_e32 v241, v158
	v_min_f32_e32 v249, 0x60ad78ec, v158
	v_exp_f32_e32 v168, v168
	v_add_f32_e32 v158, 1.0, v159
	v_mul_f32_e32 v159, 0xbfb8aa3b, v32
	v_rcp_f32_e32 v242, v158
	v_min_f32_e32 v250, 0x60ad78ec, v158
	v_add_f32_e32 v158, 1.0, v167
	v_exp_f32_e32 v159, v159
	v_mul_f32_e32 v167, 0xbfb8aa3b, v33
	v_exp_f32_e32 v167, v167
	v_rcp_f32_e32 v243, v158
	v_min_f32_e32 v251, 0x60ad78ec, v158
	v_add_f32_e32 v158, 1.0, v159
	v_rcp_f32_e32 v244, v158
	v_min_f32_e32 v252, 0x60ad78ec, v158
	v_add_f32_e32 v158, 1.0, v167
	v_mul_f32_e32 v167, 0xbfb8aa3b, v34
	v_exp_f32_e32 v167, v167
	v_rcp_f32_e32 v245, v158
	v_min_f32_e32 v253, 0x60ad78ec, v158
	v_rcp_f32_e32 v153, v153
	v_add_f32_e32 v158, 1.0, v167
	v_rcp_f32_e32 v246, v158
	v_min_f32_e32 v254, 0x60ad78ec, v158
	v_add_f32_e32 v158, 1.0, v168
	v_rcp_f32_e32 v247, v158
	v_min_f32_e32 v255, 0x60ad78ec, v158
	v_pk_mul_f32 v[154:155], v[154:155], v[248:249]
	v_pk_mul_f32 v[156:157], v[156:157], v[250:251]
	v_pk_mul_f32 v[158:159], v[152:153], v[252:253]
	v_pk_mul_f32 v[160:161], v[160:161], v[254:255]

; __device__ __forceinline__ f32x4 sigm4(f32x4 v) { return (f32x4){sigmoid_f(v[0]), sigmoid_f(v[1]), sigmoid_f(v[2]), sigmoid_f(v[3])}; }
;     __device__ __forceinline__ void operator()(const f32x4 (&acc)[2][2][4][2], const pg8::Unit& u, int wr, int wc, int fr, int fq) const {
;     ...
;                         if (act == 5) { v0 = sigm4(v0); v1 = sigm4(v1);
;                             if (bj == 0) { const f32x4 b0 = sigm4(acc[ai][1][m][0]), b1 = sigm4(acc[ai][1][m][1]);
; #pragma unroll
;                                 for (int e = 0; e < 4; ++e) { v0[e] *= __builtin_amdgcn_rcpf(fmaxf(b0[e], 1e-20f)); v1[e] *= __builtin_amdgcn_rcpf(fmaxf(b1[e], 1e-20f)); } } }
.LBB0_366:
	s_andn2_b64 vcc, exec, s[16:17]
	s_cbranch_vccnz .LBB0_368
	v_mul_f32_e32 v147, 0xbfb8aa3b, v20
	v_exp_f32_e32 v147, v147
	v_mul_f32_e32 v152, 0xbfb8aa3b, v21
	v_exp_f32_e32 v152, v152
	v_mul_f32_e32 v154, 0xbfb8aa3b, v23
	v_add_f32_e32 v147, 1.0, v147
	v_exp_f32_e32 v154, v154
	v_add_f32_e32 v153, 1.0, v152
	v_rcp_f32_e32 v152, v147
	v_mul_f32_e32 v147, 0xbfb8aa3b, v22
	v_exp_f32_e32 v147, v147
	v_mul_f32_e32 v155, 0xbfb8aa3b, v29
	v_exp_f32_e32 v155, v155
	v_mul_f32_e32 v167, 0xbfb8aa3b, v27
	v_add_f32_e32 v147, 1.0, v147
	v_rcp_f32_e32 v160, v147
	v_add_f32_e32 v147, 1.0, v154
	v_mul_f32_e32 v154, 0xbfb8aa3b, v28
	v_exp_f32_e32 v154, v154
	v_rcp_f32_e32 v161, v147
	v_exp_f32_e32 v167, v167
	v_mul_f32_e32 v168, 0xbfb8aa3b, v19
	v_add_f32_e32 v147, 1.0, v154
	v_rcp_f32_e32 v154, v147
	v_add_f32_e32 v147, 1.0, v155
	v_mul_f32_e32 v155, 0xbfb8aa3b, v30
	v_exp_f32_e32 v156, v155
	v_mul_f32_e32 v155, 0xbfb8aa3b, v31
	v_exp_f32_e32 v157, v155
	v_rcp_f32_e32 v155, v147
	v_add_f32_e32 v147, 1.0, v156
	v_rcp_f32_e32 v156, v147
	v_add_f32_e32 v147, 1.0, v157
	v_mul_f32_e32 v157, 0xbfb8aa3b, v24
	v_exp_f32_e32 v158, v157
	v_mul_f32_e32 v157, 0xbfb8aa3b, v25
	v_exp_f32_e32 v159, v157
	v_rcp_f32_e32 v157, v147
	v_add_f32_e32 v147, 1.0, v158
	v_rcp_f32_e32 v240, v147
	v_min_f32_e32 v248, 0x60ad78ec, v147
	v_add_f32_e32 v158, 1.0, v159
	v_mul_f32_e32 v159, 0xbfb8aa3b, v26
	v_exp_f32_e32 v159, v159
	v_rcp_f32_e32 v241, v158
	v_min_f32_e32 v249, 0x60ad78ec, v158
	v_exp_f32_e32 v168, v168
	v_add_f32_e32 v158, 1.0, v159
	v_mul_f32_e32 v159, 0xbfb8aa3b, v16
	v_rcp_f32_e32 v242, v158
	v_min_f32_e32 v250, 0x60ad78ec, v158
	v_add_f32_e32 v158, 1.0, v167
	v_exp_f32_e32 v159, v159
	v_mul_f32_e32 v167, 0xbfb8aa3b, v17
	v_exp_f32_e32 v167, v167
	v_rcp_f32_e32 v243, v158
	v_min_f32_e32 v251, 0x60ad78ec, v158
	v_add_f32_e32 v158, 1.0, v159
	v_rcp_f32_e32 v244, v158
	v_min_f32_e32 v252, 0x60ad78ec, v158
	v_add_f32_e32 v158, 1.0, v167
	v_mul_f32_e32 v167, 0xbfb8aa3b, v18
	v_exp_f32_e32 v167, v167
	v_rcp_f32_e32 v245, v158
	v_min_f32_e32 v253, 0x60ad78ec, v158
	v_rcp_f32_e32 v153, v153
	v_add_f32_e32 v158, 1.0, v167
	v_rcp_f32_e32 v246, v158
	v_min_f32_e32 v254, 0x60ad78ec, v158
	v_add_f32_e32 v158, 1.0, v168
	v_rcp_f32_e32 v247, v158
	v_min_f32_e32 v255, 0x60ad78ec, v158
	v_pk_mul_f32 v[154:155], v[154:155], v[248:249]
	v_pk_mul_f32 v[156:157], v[156:157], v[250:251]
	v_pk_mul_f32 v[158:159], v[152:153], v[252:253]
	v_pk_mul_f32 v[160:161], v[160:161], v[254:255]

; __device__ __forceinline__ f32x4 sigm4(f32x4 v) { return (f32x4){sigmoid_f(v[0]), sigmoid_f(v[1]), sigmoid_f(v[2]), sigmoid_f(v[3])}; }
;     __device__ __forceinline__ void operator()(const f32x4 (&acc)[2][2][4][2], const pg8::Unit& u, int wr, int wc, int fr, int fq) const {
;     ...
;                         if (act == 5) { v0 = sigm4(v0); v1 = sigm4(v1);
;                             if (bj == 0) { const f32x4 b0 = sigm4(acc[ai][1][m][0]), b1 = sigm4(acc[ai][1][m][1]);
; #pragma unroll
;                                 for (int e = 0; e < 4; ++e) { v0[e] *= __builtin_amdgcn_rcpf(fmaxf(b0[e], 1e-20f)); v1[e] *= __builtin_amdgcn_rcpf(fmaxf(b1[e], 1e-20f)); } } }
.LBB0_394:
	s_andn2_b64 vcc, exec, s[16:17]
	s_cbranch_vccnz .LBB0_396
	v_mul_f32_e32 v147, 0xbfb8aa3b, v4
	v_exp_f32_e32 v147, v147
	v_mul_f32_e32 v152, 0xbfb8aa3b, v5
	v_exp_f32_e32 v152, v152
	v_mul_f32_e32 v153, 0xbfb8aa3b, v7
	v_add_f32_e32 v147, 1.0, v147
	v_rcp_f32_e32 v156, v147
	v_mul_f32_e32 v147, 0xbfb8aa3b, v6
	v_exp_f32_e32 v147, v147
	v_exp_f32_e32 v153, v153
	v_add_f32_e32 v152, 1.0, v152
	v_rcp_f32_e32 v157, v152
	v_add_f32_e32 v147, 1.0, v147
	v_mul_f32_e32 v152, 0xbfb8aa3b, v12
	v_rcp_f32_e32 v158, v147
	v_add_f32_e32 v147, 1.0, v153
	v_exp_f32_e32 v152, v152
	v_mul_f32_e32 v153, 0xbfb8aa3b, v13
	v_exp_f32_e32 v153, v153
	v_rcp_f32_e32 v159, v147
	v_add_f32_e32 v147, 1.0, v152
	v_rcp_f32_e32 v152, v147
	v_add_f32_e32 v147, 1.0, v153
	v_mul_f32_e32 v153, 0xbfb8aa3b, v14
	v_exp_f32_e32 v154, v153
	v_mul_f32_e32 v153, 0xbfb8aa3b, v15
	v_exp_f32_e32 v155, v153
	v_rcp_f32_e32 v153, v147
	v_add_f32_e32 v147, 1.0, v154
	v_rcp_f32_e32 v154, v147
	v_add_f32_e32 v147, 1.0, v155
	v_mul_f32_e32 v155, 0xbfb8aa3b, v8
	v_exp_f32_e32 v160, v155
	v_mul_f32_e32 v155, 0xbfb8aa3b, v9
	v_exp_f32_e32 v161, v155
	v_rcp_f32_e32 v155, v147
	v_add_f32_e32 v147, 1.0, v160
	v_mul_f32_e32 v167, 0xbfb8aa3b, v11
	v_add_f32_e32 v160, 1.0, v161
	v_mul_f32_e32 v161, 0xbfb8aa3b, v10
	v_exp_f32_e32 v161, v161
	v_exp_f32_e32 v167, v167
	v_rcp_f32_e32 v241, v160
	v_min_f32_e32 v249, 0x60ad78ec, v160
	v_mul_f32_e32 v168, 0xbfb8aa3b, v3
	v_add_f32_e32 v160, 1.0, v161
	v_mul_f32_e32 v161, 0xbfb8aa3b, v0
	v_rcp_f32_e32 v242, v160
	v_min_f32_e32 v250, 0x60ad78ec, v160
	v_add_f32_e32 v160, 1.0, v167
	v_exp_f32_e32 v161, v161
	v_mul_f32_e32 v167, 0xbfb8aa3b, v1
	v_exp_f32_e32 v167, v167
	v_rcp_f32_e32 v243, v160
	v_min_f32_e32 v251, 0x60ad78ec, v160
	v_add_f32_e32 v160, 1.0, v161
	v_rcp_f32_e32 v244, v160
	v_min_f32_e32 v252, 0x60ad78ec, v160
	v_add_f32_e32 v160, 1.0, v167
	v_mul_f32_e32 v167, 0xbfb8aa3b, v2
	v_exp_f32_e32 v167, v167
	v_rcp_f32_e32 v240, v147
	v_min_f32_e32 v248, 0x60ad78ec, v147
	v_exp_f32_e32 v168, v168
	v_rcp_f32_e32 v245, v160
	v_min_f32_e32 v253, 0x60ad78ec, v160
	v_add_f32_e32 v160, 1.0, v167
	v_rcp_f32_e32 v246, v160
	v_min_f32_e32 v254, 0x60ad78ec, v160
	v_add_f32_e32 v160, 1.0, v168
	v_rcp_f32_e32 v247, v160
	v_min_f32_e32 v255, 0x60ad78ec, v160
	v_pk_mul_f32 v[152:153], v[152:153], v[248:249]
	v_pk_mul_f32 v[154:155], v[154:155], v[250:251]
	v_pk_mul_f32 v[156:157], v[156:157], v[252:253]
	v_pk_mul_f32 v[158:159], v[158:159], v[254:255]
